# c9 + P2 epilogue stores agent-scope write-through (sc1, 16-byte) and no L2 write-back (buffer_wbl2) by the XCD leader in the grid barrier after P2
# speedup vs baseline: 1.0102x; 1.0102x over previous
; __device__ __forceinline__ unsigned cvt_pk_bf16(float lo, float hi) { unsigned r; asm volatile("v_cvt_pk_bf16_f32 %0, %1, %2" : "=v"(r) : "v"(lo), "v"(hi)); return r; }
;     __device__ __forceinline__ void operator()(const f32x4 (&acc)[2][2][4][2], const Unit& u, int wr, int wc, int fr, int fq) const {
;     ...
;             for (int m = 0; m < 4; ++m) { bf16_t* rowp = base + (size_t)(row0 + ai * HALF + m * 16) * 512 + col0;
; #pragma unroll
;                 for (int bj = 0; bj < 2; ++bj) { const f32x4 v0 = acc[ai][bj][m][0], v1 = acc[ai][bj][m][1];
;                     u32x4 w; w.x = cvt_pk_bf16(v0[0], v0[1]); w.y = cvt_pk_bf16(v0[2], v0[3]); w.z = cvt_pk_bf16(v1[0], v1[1]); w.w = cvt_pk_bf16(v1[2], v1[3]);
;                     *(u32x4*)(rowp + bj * HALF) = w; } }
;         if (u.pn <= 2) {
;             float* dst = (u.pn < 2) ? ssq_q : ssq_kv;
; #pragma unroll
;             for (int ai = 0; ai < 2; ++ai)
; #pragma unroll
;                 for (int m = 0; m < 4; ++m) { float s = 0.f;
; #pragma unroll
;                     for (int bj = 0; bj < 2; ++bj)
; #pragma unroll
;                         for (int n = 0; n < 2; ++n) { const f32x4 x = acc[ai][bj][m][n]; s += (x[0] * x[0] + x[1] * x[1]) + (x[2] * x[2] + x[3] * x[3]); }
;                     s += __shfl_xor(s, 16); s += __shfl_xor(s, 32);
;                     if (fq == 0) __hip_atomic_fetch_add(dst + row0 + ai * HALF + m * 16, s, __ATOMIC_RELAXED, __HIP_MEMORY_SCOPE_AGENT); }
.LBB0_249:
	s_ashr_i32 s28, s38, 1
	s_lshl_b32 s3, s38, 8
	s_ashr_i32 s29, s28, 31
	s_and_b32 s3, s3, 0x100
	s_lshl_b64 s[28:29], s[28:29], 25
	v_lshl_add_u32 v146, s42, 8, v150
	v_or_b32_e32 v136, s3, v153
	s_add_u32 s28, s69, s28
	s_addc_u32 s29, s70, s29
	v_lshlrev_b32_e32 v136, 1, v136
	v_ashrrev_i32_e32 v147, 31, v146
	v_lshl_add_u64 v[162:163], s[28:29], 0, v[136:137]
	v_lshlrev_b64 v[148:149], 10, v[146:147]
	v_lshl_add_u64 v[148:149], v[162:163], 0, v[148:149]
	v_cvt_pk_bf16_f32 v158, v124, v125
	v_cvt_pk_bf16_f32 v159, v126, v127
	v_cvt_pk_bf16_f32 v160, v120, v121
	v_cvt_pk_bf16_f32 v161, v122, v123
	global_store_dwordx4 v[148:149], v[158:161], off sc1
	s_cmp_gt_i32 s38, 2
	s_nop 0
	v_cvt_pk_bf16_f32 v158, v116, v117
	v_cvt_pk_bf16_f32 v159, v118, v119
	v_cvt_pk_bf16_f32 v160, v112, v113
	v_cvt_pk_bf16_f32 v161, v114, v115
	global_store_dwordx4 v[148:149], v[158:161], off offset:256 sc1
	s_nop 1
	v_or_b32_e32 v158, 16, v146
	v_ashrrev_i32_e32 v159, 31, v158
	v_lshlrev_b64 v[158:159], 10, v[158:159]
	v_lshl_add_u64 v[164:165], v[162:163], 0, v[158:159]
	v_cvt_pk_bf16_f32 v158, v108, v109
	v_cvt_pk_bf16_f32 v159, v110, v111
	v_cvt_pk_bf16_f32 v160, v104, v105
	v_cvt_pk_bf16_f32 v161, v106, v107
	global_store_dwordx4 v[164:165], v[158:161], off sc1
	s_nop 1
	v_cvt_pk_bf16_f32 v158, v100, v101
	v_cvt_pk_bf16_f32 v159, v102, v103
	v_cvt_pk_bf16_f32 v160, v92, v93
	v_cvt_pk_bf16_f32 v161, v94, v95
	global_store_dwordx4 v[164:165], v[158:161], off offset:256 sc1
	s_nop 1
	v_or_b32_e32 v158, 32, v146
	v_ashrrev_i32_e32 v159, 31, v158
	v_lshlrev_b64 v[158:159], 10, v[158:159]
	v_lshl_add_u64 v[164:165], v[162:163], 0, v[158:159]
	v_cvt_pk_bf16_f32 v158, v96, v97
	v_cvt_pk_bf16_f32 v159, v98, v99
	v_cvt_pk_bf16_f32 v160, v88, v89
	v_cvt_pk_bf16_f32 v161, v90, v91
	global_store_dwordx4 v[164:165], v[158:161], off sc1
	s_nop 1
	v_cvt_pk_bf16_f32 v158, v84, v85
	v_cvt_pk_bf16_f32 v159, v86, v87
	v_cvt_pk_bf16_f32 v160, v76, v77
	v_cvt_pk_bf16_f32 v161, v78, v79
	global_store_dwordx4 v[164:165], v[158:161], off offset:256 sc1
	v_add_co_u32_e32 v164, vcc, s89, v148
	s_nop 0
	v_or_b32_e32 v158, 48, v146
	v_ashrrev_i32_e32 v159, 31, v158
	v_lshlrev_b64 v[158:159], 10, v[158:159]
	v_lshl_add_u64 v[162:163], v[162:163], 0, v[158:159]
	v_cvt_pk_bf16_f32 v158, v80, v81
	v_cvt_pk_bf16_f32 v159, v82, v83
	v_cvt_pk_bf16_f32 v160, v72, v73
	v_cvt_pk_bf16_f32 v161, v74, v75
	global_store_dwordx4 v[162:163], v[158:161], off sc1
	v_addc_co_u32_e32 v165, vcc, 0, v149, vcc
	s_nop 0
	v_cvt_pk_bf16_f32 v158, v68, v69
	v_cvt_pk_bf16_f32 v159, v70, v71
	v_cvt_pk_bf16_f32 v160, v64, v65
	v_cvt_pk_bf16_f32 v161, v66, v67
	global_store_dwordx4 v[162:163], v[158:161], off offset:256 sc1
	v_lshl_add_u64 v[162:163], v[148:149], 0, s[14:15]
	s_nop 0
	v_cvt_pk_bf16_f32 v158, v60, v61
	v_cvt_pk_bf16_f32 v159, v62, v63
	v_cvt_pk_bf16_f32 v160, v56, v57
	v_cvt_pk_bf16_f32 v161, v58, v59
	global_store_dwordx4 v[164:165], v[158:161], off sc1
	v_add_co_u32_e32 v164, vcc, s90, v148
	s_nop 0
	v_cvt_pk_bf16_f32 v158, v52, v53
	v_cvt_pk_bf16_f32 v159, v54, v55
	v_cvt_pk_bf16_f32 v160, v44, v45
	v_cvt_pk_bf16_f32 v161, v46, v47
	global_store_dwordx4 v[162:163], v[158:161], off offset:256 sc1
	v_addc_co_u32_e32 v165, vcc, 0, v149, vcc
	s_nop 0
	v_cvt_pk_bf16_f32 v158, v48, v49
	v_cvt_pk_bf16_f32 v159, v50, v51
	v_cvt_pk_bf16_f32 v160, v40, v41
	v_cvt_pk_bf16_f32 v161, v42, v43
	v_lshl_add_u64 v[162:163], v[148:149], 0, s[16:17]
	global_store_dwordx4 v[164:165], v[158:161], off sc1
	v_add_co_u32_e32 v164, vcc, s91, v148
	s_nop 0
	v_cvt_pk_bf16_f32 v158, v36, v37
	v_cvt_pk_bf16_f32 v159, v38, v39
	v_cvt_pk_bf16_f32 v160, v28, v29
	v_cvt_pk_bf16_f32 v161, v30, v31
	global_store_dwordx4 v[162:163], v[158:161], off offset:256 sc1
	v_lshl_add_u64 v[162:163], v[148:149], 0, s[18:19]
	v_addc_co_u32_e32 v165, vcc, 0, v149, vcc
	v_cvt_pk_bf16_f32 v158, v32, v33
	v_cvt_pk_bf16_f32 v159, v34, v35
	v_cvt_pk_bf16_f32 v160, v24, v25
	v_cvt_pk_bf16_f32 v161, v26, v27
	global_store_dwordx4 v[164:165], v[158:161], off sc1
	s_nop 1
	v_cvt_pk_bf16_f32 v158, v20, v21
	v_cvt_pk_bf16_f32 v159, v22, v23
	v_cvt_pk_bf16_f32 v160, v12, v13
	v_cvt_pk_bf16_f32 v161, v14, v15
	global_store_dwordx4 v[162:163], v[158:161], off offset:256 sc1
	v_lshl_add_u64 v[162:163], v[148:149], 0, s[20:21]
	v_add_co_u32_e32 v148, vcc, s92, v148
	v_cvt_pk_bf16_f32 v158, v16, v17
	v_cvt_pk_bf16_f32 v159, v18, v19
	v_cvt_pk_bf16_f32 v160, v8, v9
	v_cvt_pk_bf16_f32 v161, v10, v11
	s_nop 1
	v_addc_co_u32_e32 v149, vcc, 0, v149, vcc
	global_store_dwordx4 v[148:149], v[158:161], off sc1
	s_nop 1
	v_cvt_pk_bf16_f32 v158, v4, v5
	v_cvt_pk_bf16_f32 v159, v6, v7
	v_cvt_pk_bf16_f32 v160, v0, v1
	v_cvt_pk_bf16_f32 v161, v2, v3
	global_store_dwordx4 v[162:163], v[158:161], off offset:256 sc1
	s_cbranch_scc1 .LBB0_267
	v_mul_f32_e32 v125, v125, v125
	v_mul_f32_e32 v121, v121, v121
	v_fmac_f32_e32 v125, v124, v124
	v_mul_f32_e32 v124, v127, v127
	v_fmac_f32_e32 v121, v120, v120
	v_mul_f32_e32 v120, v123, v123
	v_mul_f32_e32 v117, v117, v117
	v_and_b32_e32 v148, 64, v157
	v_fmac_f32_e32 v124, v126, v126
	v_fmac_f32_e32 v120, v122, v122
	v_fmac_f32_e32 v117, v116, v116
	v_mul_f32_e32 v116, v119, v119
	v_mul_f32_e32 v113, v113, v113
	v_xor_b32_e32 v136, 16, v157
	v_add_u32_e32 v148, 64, v148
	v_add_f32_e32 v124, v125, v124
	v_add_f32_e32 v120, v121, v120
	v_fmac_f32_e32 v116, v118, v118
	v_fmac_f32_e32 v113, v112, v112
	v_mul_f32_e32 v112, v115, v115
	v_cmp_lt_i32_e32 vcc, v136, v148
	v_add_f32_e32 v120, v124, v120
	v_add_f32_e32 v116, v117, v116
	v_fmac_f32_e32 v112, v114, v114
	v_cndmask_b32_e32 v136, v157, v136, vcc
	v_add_f32_e32 v116, v120, v116
	v_add_f32_e32 v112, v113, v112
	v_lshlrev_b32_e32 v136, 2, v136
	v_add_f32_e32 v112, v116, v112
	ds_bpermute_b32 v113, v136, v112
	v_xor_b32_e32 v114, 32, v157
	v_cmp_lt_i32_e32 vcc, v114, v148
	s_cmp_eq_u32 s38, 2
	s_cselect_b32 s3, s93, 0x200000
	v_cndmask_b32_e32 v114, v157, v114, vcc
	v_lshlrev_b32_e32 v114, 2, v114
	s_waitcnt lgkmcnt(0)
	v_add_f32_e32 v115, v112, v113
	ds_bpermute_b32 v116, v114, v115
	s_add_u32 s28, s30, s3
	s_addc_u32 s29, s31, 0
	v_lshl_add_u64 v[112:113], v[146:147], 2, s[28:29]
	s_and_saveexec_b64 s[38:39], s[4:5]
	s_cbranch_execz .LBB0_252
	s_waitcnt lgkmcnt(0)
	v_add_f32_e32 v115, v115, v116
	global_atomic_add_f32 v[112:113], v115, off

; __device__ __forceinline__ unsigned xb_add(unsigned* p, unsigned v) { return __hip_atomic_fetch_add(p, v, __ATOMIC_RELAXED, __HIP_MEMORY_SCOPE_AGENT); }
; __device__ __forceinline__ void xcd_barrier(const XcdBarrier& b) {
;     ...
;         if (old + 1u == (gen + 1u) * nloc) {
;             __builtin_amdgcn_fence(__ATOMIC_RELEASE, "agent");
;             asm volatile("s_waitcnt vmcnt(0)" ::: "memory");
;             const unsigned og = xb_add(&bar[XB_TOP], 1u);
.LBB0_303:
	s_andn2_saveexec_b64 s[8:9], s[8:9]
	s_cbranch_execz .LBB0_323
	s_mov_b64 s[8:9], exec
	s_waitcnt lgkmcnt(0)
	s_waitcnt vmcnt(0)
	v_mbcnt_lo_u32_b32 v1, s8, 0
	v_mbcnt_hi_u32_b32 v1, s9, v1
	v_cmp_eq_u32_e32 vcc, 0, v1
	s_and_saveexec_b64 s[10:11], vcc
	s_cbranch_execz .LBB0_306
	s_bcnt1_i32_b64 s3, s[8:9]
	v_mov_b32_e32 v2, 0x83000
	v_mov_b32_e32 v3, s3
	global_atomic_add v2, v2, v3, s[30:31] offset:1024 sc0
